# unit start: sink-logit load no longer drains all VMEM at decode; conservative vmcnt(0) behind the V0 LDS-DMA issue dropped so it flies under step 0
# speedup vs baseline: 1.0118x; 1.0051x over previous
; __global__ void __launch_bounds__(NWAVES * 64, 2) mk_fwd(Args args) {
;     ...
;                         const int ui = v * 4 + (i - 8), hq = (ui >> 5) & 7, b = ui >> 8; qb = ui & 31; t0 = qb > 0 ? 4 * qb - 2 : 0; win = true; rowbase = (long)b * SEQ;
;                         qc = hq * 64; kc = 512 + (hq >> 2) * 64; vc = 640 + (hq >> 2) * 64; oc = hq * 64; Ob = OA;
;                         s2 = exp2f(-8.0f * (float)(1 + hq) / 12.0f) * LOG2E; sink2 = ap->in[9][l * 8 + hq] * LOG2E;
.LBB0_258:
	s_xor_b64 s[40:41], s[38:39], -1
	s_and_b64 vcc, exec, s[44:45]
	v_mov_b32_e32 v235, 0xff800000
	v_mov_b32_e32 v51, v179
	s_mov_b64 s[52:53], s[56:57]
	v_mov_b32_e32 v34, v182
	s_mov_b32 s90, s33
	s_mov_b32 s38, s91
	s_mov_b32 s39, s89
	s_mov_b32 s49, s88
	s_cbranch_vccz .LBB0_260
	s_add_i32 s4, s3, s85
	s_and_b32 s2, s4, 127
	s_ashr_i32 s42, s4, 8
	s_bfe_u32 s43, s4, 0x10007
	s_add_i32 s38, s2, -3
	s_max_i32 s48, s38, 0
	v_readfirstlane_b32 s100, v234
	s_lshr_b32 s100, s100, 6
	s_lshl_b32 s4, s43, 6
	s_or_b32 s39, s4, 0x200
	s_or_b32 s38, s4, 0x280
	s_lshl_b32 s43, s43, 2
	s_and_b32 s101, s100, 3
	s_or_b32 s43, s43, s101
	s_not_b32 s4, s43
	s_lshl_b32 s4, s4, 3
	v_cvt_f32_i32_e32 v0, s4
	s_mov_b32 s4, 0x41400000
	s_lshl_b32 s90, s43, 6
	s_mov_b64 s[52:53], 0x13000000
	v_div_scale_f32 v2, s[44:45], s4, s4, v0
	v_rcp_f32_e32 v3, v2
	v_mov_b32_e32 v51, v178
	s_mov_b32 s49, s90
	v_fma_f32 v4, -v2, v3, 1.0
	v_fmac_f32_e32 v3, v4, v3
	v_div_scale_f32 v4, vcc, v0, s4, v0
	v_mul_f32_e32 v5, v4, v3
	v_fma_f32 v6, -v2, v5, v4
	v_fmac_f32_e32 v5, v6, v3
	v_fma_f32 v2, -v2, v5, v4
	v_div_fmas_f32 v2, v2, v3, v5
	v_div_fixup_f32 v0, v2, s4, v0
	s_mov_b32 s4, 0xc2fc0000
	v_cmp_gt_f32_e32 vcc, s4, v0
	s_and_b64 s[44:45], vcc, exec
	s_load_dwordx2 s[44:45], s[46:47], 0x48
	v_cndmask_b32_e32 v2, 0, v216, vcc
	v_add_f32_e32 v0, v0, v2
	v_exp_f32_e32 v0, v0
	s_cselect_b32 s4, 0xffffffc0, 0
	v_ldexp_f32 v34, v0, s4
	s_or_b32 s4, s43, s74
	s_lshl_b64 s[50:51], s[4:5], 2
	s_waitcnt lgkmcnt(0)
	s_add_u32 s44, s44, s50
	s_addc_u32 s45, s45, s51
	global_load_dword v235, v1, s[44:45]
	s_nop 0
	s_mov_b32 s100, 2
	s_mov_b32 s101, 6

; #define WAIT_BAR(N) asm volatile("s_waitcnt vmcnt(" #N ") lgkmcnt(0)\n\ts_barrier":::"memory")
;   #define DMA_K(t,slot) glds16(ksrc+(long)(t)*KVBLK*PIN,(unsigned)__builtin_amdgcn_readfirstlane(kdst+(slot)))
;   #define DMA_V(t,slot) glds16(vsrc+(long)(t)*KVBLK*PIN,(unsigned)__builtin_amdgcn_readfirstlane(vdst+(slot)))
;   #define CINIT(C0,C1,btl) do{ const float b_=(btl); _Pragma("unroll") for(int r=0;r<16;++r){ C0[r]=__builtin_fmaf(s2,(float)((r&3)+8*(r>>2)),b_); C1[r]=__builtin_fmaf(s2,(float)((r&3)+8*(r>>2)+32),b_);} }while(0)
;   #define ROT() do{sl_prev=sl_cur;sl_cur=sl_next;sl_next=(sl_next==(NSLOT-1)*SLOTB)?0:sl_next+SLOTB;}while(0)
; template<int THRL> __device__ __forceinline__ void attn_unit(long rowbase,int qb,int t0,bool WIN,bool NOMAX,const bf16*Qc,const bf16*__restrict__ Kc,const bf16*__restrict__ Vc,bf16*Oc,float s2,float sink2,char*shm,
;     bf16x8 (&qr)[4],bool pref,const bf16*qkvb,int vn,int in_){
;     ...
;   _Pragma("unroll") for(int r=0;r<16;++r)pA1[r]=__builtin_amdgcn_exp2f(pA1[r]);
;   WAIT_BAR(0);
;   DMA_K(3,0);DMA_V(1,SLOTB);
;   ROT();
;   kload8(kf,kp0+sl_cur);
;   CINIT(pB0,pB1,__builtin_fmaf(s2,64.f,-qb2)-mhat); asm volatile("":"+v"(pB0)); asm volatile("":"+v"(pB1));
;   WAIT_BAR(2);
.LBB0_332:
	s_or_b64 exec, exec, s[42:43]
	s_and_b32 s42, s44, 0x3fffffc0
	s_lshl_b32 s42, s42, 2
	s_add_i32 s44, s42, 0
	s_waitcnt vmcnt(0) lgkmcnt(0)
	s_barrier
	v_mul_f32_e32 v235, 0x3fb8aa3b, v235
	s_mov_b64 s[64:65], 0xd8000
	v_exp_f32_e32 v114, v18
	v_exp_f32_e32 v115, v19
	v_lshl_add_u64 v[18:19], v[194:195], 0, s[64:65]
	s_mov_b32 s42, m0
	s_mov_b32 m0, s50
	s_nop 0
	global_load_lds_dwordx4 v[18:19], off
	s_mov_b32 m0, s42
	s_cmp_lg_u32 0, -1
	s_cselect_b32 s42, 0, 0
	s_add_i32 s42, s42, s82
	v_lshl_add_u64 v[192:193], v[82:83], 0, s[6:7]
	s_add_i32 s42, s42, 0x8000
	s_mov_b32 s43, m0
	s_mov_b32 m0, s42
	s_nop 0
	global_load_lds_dwordx4 v[192:193], off
	s_add_i32 m0, s42, 0xe780
	s_nop 0
	global_load_lds_dwordx4 v[192:193], off offset:128
	s_mov_b32 m0, s43
	ds_read_b128 v[174:177], v231 offset:8192
	ds_read_b128 v[170:173], v231 offset:8704
	ds_read_b128 v[166:169], v231 offset:10240
	ds_read_b128 v[162:165], v231 offset:10752
	ds_read_b128 v[158:161], v231 offset:12288
	ds_read_b128 v[154:157], v231 offset:12800
	ds_read_b128 v[150:153], v231 offset:14336
	ds_read_b128 v[146:149], v231 offset:14848
	v_lshlrev_b32_e32 v51, 1, v50
	v_lshrrev_b32_e32 v50, 2, v50
	v_and_b32_e32 v229, 32, v51
	v_and_or_b32 v50, v50, 3, v230
	v_fmamk_f32 v18, v184, 0x42800000, v186
	v_lshlrev_b32_e32 v226, 6, v50
	v_add_u32_e32 v50, 0, v229
	v_sub_f32_e32 v18, v18, v225
	v_mov_b32_e32 v185, v184
	v_add3_u32 v232, v50, v219, v226
	v_exp_f32_e32 v116, v20
	v_exp_f32_e32 v117, v21
	v_exp_f32_e32 v118, v22
	v_exp_f32_e32 v119, v23
	v_exp_f32_e32 v120, v24
	v_exp_f32_e32 v121, v25
	v_exp_f32_e32 v122, v26
	v_exp_f32_e32 v123, v27
	v_exp_f32_e32 v124, v28
	v_exp_f32_e32 v125, v29
	v_exp_f32_e32 v126, v30
	v_exp_f32_e32 v127, v31
	v_exp_f32_e32 v128, v32
	v_exp_f32_e32 v129, v33
	v_exp_f32_e32 v98, v34
	v_exp_f32_e32 v99, v35
	v_exp_f32_e32 v100, v36
	v_exp_f32_e32 v101, v37
	v_exp_f32_e32 v102, v38
	v_exp_f32_e32 v103, v39
	v_exp_f32_e32 v104, v40
	v_exp_f32_e32 v105, v41
	v_exp_f32_e32 v106, v42
	v_exp_f32_e32 v107, v43
	v_exp_f32_e32 v108, v44
	v_exp_f32_e32 v109, v45
	v_exp_f32_e32 v110, v46
	v_exp_f32_e32 v111, v47
	v_exp_f32_e32 v112, v48
	v_exp_f32_e32 v113, v49
	v_fma_f32 v66, 0, v184, v18
	v_add_f32_e32 v67, v184, v18
	v_fma_f32 v69, v191, s9, v18
	v_fma_f32 v68, v190, s8, v18
	v_fma_f32 v71, v191, s11, v18
	v_fma_f32 v70, v190, s10, v18
	v_fma_f32 v73, v191, s13, v18
	v_fma_f32 v72, v190, s12, v18
	v_fma_f32 v75, v191, s15, v18
	v_fma_f32 v74, v190, s14, v18
	v_fma_f32 v77, v191, s17, v18
	v_fma_f32 v76, v190, s16, v18
	v_fma_f32 v79, v191, s19, v18
	v_fma_f32 v78, v190, s18, v18
	v_fma_f32 v81, v191, s21, v18
	v_fma_f32 v80, v190, s20, v18
	v_fma_f32 v65, v185, s23, v18
	v_fma_f32 v64, v184, s22, v18
	v_fma_f32 v63, v185, s25, v18
	v_fma_f32 v62, v184, s24, v18
	v_fma_f32 v61, v185, s27, v18
	v_fma_f32 v60, v184, s26, v18
	v_fma_f32 v59, v185, s29, v18
	v_fma_f32 v58, v184, s28, v18
	v_fma_f32 v57, v185, s31, v18
	v_fma_f32 v56, v184, s30, v18
	v_fma_f32 v55, v185, s35, v18
	v_fma_f32 v54, v184, s34, v18
	v_fma_f32 v53, v185, s37, v18
	v_fma_f32 v52, v184, s36, v18
	v_fma_f32 v51, v189, s93, v18
	v_fma_f32 v50, v188, s92, v18
	s_mov_b32 s67, 1
	s_waitcnt vmcnt(3) lgkmcnt(0)
	s_barrier
	v_mov_b32_e32 v236, 0
	v_mov_b32_e32 v237, 0
	v_mov_b32_e32 v238, 0
	v_mov_b32_e32 v239, 0
	v_mov_b32_e32 v240, 0
	v_mov_b32_e32 v241, 0
	v_mov_b32_e32 v242, 0
	v_mov_b32_e32 v243, 0
	v_mov_b32_e32 v244, 0
	v_mov_b32_e32 v245, 0
	v_mov_b32_e32 v246, 0
	v_mov_b32_e32 v247, 0
	v_mov_b32_e32 v248, 0
	v_mov_b32_e32 v249, 0
	v_mov_b32_e32 v250, 0
	v_mov_b32_e32 v251, 0
	v_mov_b32_e32 v200, 0
	v_mov_b32_e32 v201, 0
	v_mov_b32_e32 v202, 0
	v_mov_b32_e32 v203, 0
	v_mov_b32_e32 v204, 0
	v_mov_b32_e32 v205, 0
	v_mov_b32_e32 v206, 0
	v_mov_b32_e32 v207, 0
	v_mov_b32_e32 v208, 0
	v_mov_b32_e32 v209, 0
	v_mov_b32_e32 v210, 0
	v_mov_b32_e32 v211, 0
	v_mov_b32_e32 v212, 0
	v_mov_b32_e32 v213, 0
	v_mov_b32_e32 v214, 0
	v_mov_b32_e32 v215, 0
	s_mov_b32 s66, 0
	s_cmp_lt_i32 s4, 7
	v_cmp_gt_u32_e64 s[42:43], 32, v183
	v_lshl_add_u32 v228, v180, 2, s44
	v_lshl_add_u32 v227, v230, 2, s44
	s_cbranch_scc1 .LBB0_355
	v_mov_b32_e32 v32, v1
	v_mov_b32_e32 v33, v1
	s_mov_b64 s[44:45], 0x168000
	v_mov_b32_e32 v18, v1
	v_mov_b32_e32 v19, v1
	v_mov_b32_e32 v20, v1
	v_mov_b32_e32 v21, v1
	v_mov_b32_e32 v22, v1
	v_mov_b32_e32 v23, v1
	v_mov_b32_e32 v24, v1
	v_mov_b32_e32 v25, v1
	v_mov_b32_e32 v26, v1
	v_mov_b32_e32 v27, v1
	v_mov_b32_e32 v28, v1
	v_mov_b32_e32 v29, v1
	v_mov_b32_e32 v30, v1
	v_mov_b32_e32 v31, v1
	v_mov_b64_e32 v[48:49], v[32:33]
	s_add_i32 s48, s4, -5
	v_lshl_add_u64 v[196:197], v[82:83], 0, s[64:65]
	v_lshl_add_u64 v[198:199], v[194:195], 0, s[44:45]
	s_mov_b32 s44, 0
	s_movk_i32 s66, 0x4000
	s_movk_i32 s51, 0x2000
	v_mov_b32_e32 v82, 0
	s_movk_i32 s49, 0xc0
	v_mov_b64_e32 v[46:47], v[30:31]
	v_mov_b64_e32 v[44:45], v[28:29]
	v_mov_b64_e32 v[42:43], v[26:27]
	v_mov_b64_e32 v[40:41], v[24:25]
	v_mov_b64_e32 v[38:39], v[22:23]
	v_mov_b64_e32 v[36:37], v[20:21]
	v_mov_b64_e32 v[34:35], v[18:19]

;   #define DMA_K(t,slot) glds16(ksrc+(long)(t)*KVBLK*PIN,(unsigned)__builtin_amdgcn_readfirstlane(kdst+(slot)))
;   #define DMA_V(t,slot) glds16(vsrc+(long)(t)*KVBLK*PIN,(unsigned)__builtin_amdgcn_readfirstlane(vdst+(slot)))
;   #define PIN(x) asm volatile("":"+v"(x))
; template<int THRL> __device__ __forceinline__ void attn_unit(long rowbase,int qb,int t0,bool WIN,bool NOMAX,const bf16*Qc,const bf16*__restrict__ Kc,const bf16*__restrict__ Vc,bf16*Oc,float s2,float sink2,char*shm,
;     bf16x8 (&qr)[4],bool pref,const bf16*qkvb,int vn,int in_){
;     ...
;   if(!pref){ DMA_K(0,0);DMA_V(0,0);DMA_K(1,SLOTB);
;     _Pragma("unroll") for(int d0=0;d0<4;++d0)qr[d0]=*reinterpret_cast<const bf16x8*>(&Qw[(long)r32*PIN+d0*16+hi*8]);
;   } else { DMA_V(0,0); }
.LBB0_353:
	s_mov_b32 s40, m0
	s_mov_b32 m0, s79
	s_nop 0
	global_load_lds_dwordx4 v[82:83], off
	s_add_i32 m0, s79, 0xe780
	s_nop 0
	global_load_lds_dwordx4 v[82:83], off offset:128
	s_mov_b32 m0, s40
	v_mov_b64_e32 v[2:3], v[18:19]
	v_mov_b64_e32 v[4:5], v[20:21]
	v_mov_b64_e32 v[6:7], v[22:23]
	v_mov_b64_e32 v[8:9], v[24:25]
	v_mov_b64_e32 v[10:11], v[26:27]
	v_mov_b64_e32 v[12:13], v[28:29]
	v_mov_b64_e32 v[14:15], v[30:31]
	v_mov_b64_e32 v[16:17], v[32:33]
	s_and_b64 vcc, exec, s[38:39]
	s_mov_b64 s[38:39], -1
	s_cbranch_vccnz .LBB0_263
